# SwiGLU epilogue polish: trans-to-VALU wait states filled with the previous pair's cvt, one 64-bit mad for the store base then literal row offsets
# speedup vs baseline: 1.0069x; 1.0069x over previous
; __device__ __forceinline__ unsigned cvt_pk_bf16(float lo, float hi) { unsigned r; asm volatile("v_cvt_pk_bf16_f32 %0, %1, %2" : "=v"(r) : "v"(lo), "v"(hi)); return r; }
;     __device__ __forceinline__ void operator()(const f32x4 (&acc)[2][2][4][2], const Unit& u, int wr, int wc, int fr, int fq) const {
;         const int row0 = u.pm * BM + u.roff + wr * 64 + fr, col0 = u.pn * HALF + wc * 32 + 8 * fq;
; #pragma unroll
;         for (int ai = 0; ai < NAI; ++ai)
; #pragma unroll
;             for (int m = 0; m < 4; ++m) {
;                 const int row = row0 + ai * HALF + m * 16; const float ri = tab[u.par * 256 + ai * HALF + wr * 64 + m * 16 + fr];
;                 const f32x4 g0 = acc[ai][0][m][0] * ri, g1 = acc[ai][0][m][1] * ri, u0 = acc[ai][1][m][0] * ri, u1 = acc[ai][1][m][1] * ri;
;                 u32x4 w;
;                 w.x = pg8::cvt_pk_bf16(silu_mul(g0[0], u0[0]), silu_mul(g0[1], u0[1])); w.y = pg8::cvt_pk_bf16(silu_mul(g0[2], u0[2]), silu_mul(g0[3], u0[3]));
;                 w.z = pg8::cvt_pk_bf16(silu_mul(g1[0], u1[0]), silu_mul(g1[1], u1[1])); w.w = pg8::cvt_pk_bf16(silu_mul(g1[2], u1[2]), silu_mul(g1[3], u1[3]));
;                 *(u32x4*)(O + (size_t)row * DFF + col0) = w;
.LBB0_185:
	v_lshl_add_u32 v147, s55, 10, v145
	ds_read_b32 v202, v147
	ds_read_b32 v203, v147 offset:64
	ds_read_b32 v204, v147 offset:128
	ds_read_b32 v205, v147 offset:192
	ds_read_b32 v206, v147 offset:512
	ds_read_b32 v207, v147 offset:576
	ds_read_b32 v208, v147 offset:640
	ds_read_b32 v209, v147 offset:704
	v_readlane_b32 s18, v254, 11
	v_lshl_or_b32 v140, s56, 7, v144
	v_readlane_b32 s19, v254, 12
	v_lshl_add_u32 v148, s57, 8, v142
	v_ashrrev_i32_e32 v141, 31, v140
	v_lshlrev_b64 v[210:211], 1, v[140:141]
	s_nop 1
	v_mov_b64_e32 v[212:213], s[18:19]
	v_mad_i64_i32 v[212:213], s[18:19], v148, s41, v[212:213]
	v_lshl_add_u64 v[212:213], v[212:213], 0, v[210:211]
	s_waitcnt lgkmcnt(0)
	v_mul_f32_e32 v214, 0xbfb8aa3b, v202
	v_mul_f32_e32 v220, v202, v202
	v_mul_f32_e32 v216, v126, v214
	v_mul_f32_e32 v217, v127, v214
	v_exp_f32_e32 v216, v216
	v_exp_f32_e32 v217, v217
	v_pk_mul_f32 v[218:219], v[126:127], v[118:119]
	v_pk_add_f32 v[216:217], v[216:217], 1.0 op_sel_hi:[1,0]
	v_pk_mul_f32 v[218:219], v[218:219], v[220:221] op_sel_hi:[1,0]
	v_rcp_f32_e32 v216, v216
	v_rcp_f32_e32 v217, v217
	s_nop 0
	v_pk_mul_f32 v[218:219], v[218:219], v[216:217]
	v_mul_f32_e32 v216, v128, v214
	v_mul_f32_e32 v217, v129, v214
	v_exp_f32_e32 v216, v216
	v_exp_f32_e32 v217, v217
	v_pk_mul_f32 v[230:231], v[128:129], v[120:121]
	v_pk_add_f32 v[216:217], v[216:217], 1.0 op_sel_hi:[1,0]
	v_pk_mul_f32 v[230:231], v[230:231], v[220:221] op_sel_hi:[1,0]
	v_rcp_f32_e32 v216, v216
	v_rcp_f32_e32 v217, v217
	v_cvt_pk_bf16_f32 v226, v218, v219
	v_pk_mul_f32 v[230:231], v[230:231], v[216:217]
	v_mul_f32_e32 v216, v122, v214
	v_mul_f32_e32 v217, v123, v214
	v_exp_f32_e32 v216, v216
	v_exp_f32_e32 v217, v217
	v_pk_mul_f32 v[218:219], v[122:123], v[114:115]
	v_pk_add_f32 v[216:217], v[216:217], 1.0 op_sel_hi:[1,0]
	v_pk_mul_f32 v[218:219], v[218:219], v[220:221] op_sel_hi:[1,0]
	v_rcp_f32_e32 v216, v216
	v_rcp_f32_e32 v217, v217
	v_cvt_pk_bf16_f32 v227, v230, v231
	v_pk_mul_f32 v[218:219], v[218:219], v[216:217]
	v_mul_f32_e32 v216, v124, v214
	v_mul_f32_e32 v217, v125, v214
	v_exp_f32_e32 v216, v216
	v_exp_f32_e32 v217, v217
	v_pk_mul_f32 v[230:231], v[124:125], v[116:117]
	v_pk_add_f32 v[216:217], v[216:217], 1.0 op_sel_hi:[1,0]
	v_pk_mul_f32 v[230:231], v[230:231], v[220:221] op_sel_hi:[1,0]
	v_rcp_f32_e32 v216, v216
	v_rcp_f32_e32 v217, v217
	v_cvt_pk_bf16_f32 v228, v218, v219
	v_pk_mul_f32 v[230:231], v[230:231], v[216:217]
	v_cvt_pk_bf16_f32 v229, v230, v231
	global_store_dwordx4 v[212:213], v[226:229], off
	v_mul_f32_e32 v214, 0xbfb8aa3b, v203
	v_mul_f32_e32 v220, v203, v203
	v_mul_f32_e32 v216, v110, v214
	v_mul_f32_e32 v217, v111, v214
	v_exp_f32_e32 v216, v216
	v_exp_f32_e32 v217, v217
	v_pk_mul_f32 v[218:219], v[110:111], v[102:103]
	v_pk_add_f32 v[216:217], v[216:217], 1.0 op_sel_hi:[1,0]
	v_pk_mul_f32 v[218:219], v[218:219], v[220:221] op_sel_hi:[1,0]
	v_rcp_f32_e32 v216, v216
	v_rcp_f32_e32 v217, v217
	s_nop 0
	v_pk_mul_f32 v[218:219], v[218:219], v[216:217]
	v_mul_f32_e32 v216, v112, v214
	v_mul_f32_e32 v217, v113, v214
	v_exp_f32_e32 v216, v216
	v_exp_f32_e32 v217, v217
	v_pk_mul_f32 v[230:231], v[112:113], v[104:105]
	v_pk_add_f32 v[216:217], v[216:217], 1.0 op_sel_hi:[1,0]
	v_pk_mul_f32 v[230:231], v[230:231], v[220:221] op_sel_hi:[1,0]
	v_rcp_f32_e32 v216, v216
	v_rcp_f32_e32 v217, v217
	v_cvt_pk_bf16_f32 v226, v218, v219
	v_pk_mul_f32 v[230:231], v[230:231], v[216:217]
	v_mul_f32_e32 v216, v106, v214
	v_mul_f32_e32 v217, v107, v214
	v_exp_f32_e32 v216, v216
	v_exp_f32_e32 v217, v217
	v_pk_mul_f32 v[218:219], v[106:107], v[98:99]
	v_pk_add_f32 v[216:217], v[216:217], 1.0 op_sel_hi:[1,0]
	v_pk_mul_f32 v[218:219], v[218:219], v[220:221] op_sel_hi:[1,0]
	v_rcp_f32_e32 v216, v216
	v_rcp_f32_e32 v217, v217
	v_cvt_pk_bf16_f32 v227, v230, v231
	v_pk_mul_f32 v[218:219], v[218:219], v[216:217]
	v_mul_f32_e32 v216, v108, v214
	v_mul_f32_e32 v217, v109, v214
	v_exp_f32_e32 v216, v216
	v_exp_f32_e32 v217, v217
	v_pk_mul_f32 v[230:231], v[108:109], v[100:101]
	v_pk_add_f32 v[216:217], v[216:217], 1.0 op_sel_hi:[1,0]
	v_pk_mul_f32 v[230:231], v[230:231], v[220:221] op_sel_hi:[1,0]
	v_rcp_f32_e32 v216, v216
	v_rcp_f32_e32 v217, v217
	v_cvt_pk_bf16_f32 v228, v218, v219
	v_pk_mul_f32 v[230:231], v[230:231], v[216:217]
	v_cvt_pk_bf16_f32 v229, v230, v231
	v_add_co_u32_e32 v224, vcc, 0x16000, v212
	v_addc_co_u32_e32 v225, vcc, 0, v213, vcc
	global_store_dwordx4 v[224:225], v[226:229], off
	v_mul_f32_e32 v214, 0xbfb8aa3b, v204
	v_mul_f32_e32 v220, v204, v204
	v_mul_f32_e32 v216, v94, v214
	v_mul_f32_e32 v217, v95, v214
	v_exp_f32_e32 v216, v216
	v_exp_f32_e32 v217, v217
	v_pk_mul_f32 v[218:219], v[94:95], v[86:87]
	v_pk_add_f32 v[216:217], v[216:217], 1.0 op_sel_hi:[1,0]
	v_pk_mul_f32 v[218:219], v[218:219], v[220:221] op_sel_hi:[1,0]
	v_rcp_f32_e32 v216, v216
	v_rcp_f32_e32 v217, v217
	s_nop 0
	v_pk_mul_f32 v[218:219], v[218:219], v[216:217]
	v_mul_f32_e32 v216, v96, v214
	v_mul_f32_e32 v217, v97, v214
	v_exp_f32_e32 v216, v216
	v_exp_f32_e32 v217, v217
	v_pk_mul_f32 v[230:231], v[96:97], v[88:89]
	v_pk_add_f32 v[216:217], v[216:217], 1.0 op_sel_hi:[1,0]
	v_pk_mul_f32 v[230:231], v[230:231], v[220:221] op_sel_hi:[1,0]
	v_rcp_f32_e32 v216, v216
	v_rcp_f32_e32 v217, v217
	v_cvt_pk_bf16_f32 v226, v218, v219
	v_pk_mul_f32 v[230:231], v[230:231], v[216:217]
	v_mul_f32_e32 v216, v90, v214
	v_mul_f32_e32 v217, v91, v214
	v_exp_f32_e32 v216, v216
	v_exp_f32_e32 v217, v217
	v_pk_mul_f32 v[218:219], v[90:91], v[82:83]
	v_pk_add_f32 v[216:217], v[216:217], 1.0 op_sel_hi:[1,0]
	v_pk_mul_f32 v[218:219], v[218:219], v[220:221] op_sel_hi:[1,0]
	v_rcp_f32_e32 v216, v216
; __device__ __forceinline__ unsigned cvt_pk_bf16(float lo, float hi) { unsigned r; asm volatile("v_cvt_pk_bf16_f32 %0, %1, %2" : "=v"(r) : "v"(lo), "v"(hi)); return r; }
;     __device__ __forceinline__ void operator()(const f32x4 (&acc)[2][2][4][2], const Unit& u, int wr, int wc, int fr, int fq) const {
;     ...
;             for (int m = 0; m < 4; ++m) {
;                 const int row = row0 + ai * HALF + m * 16; const float ri = tab[u.par * 256 + ai * HALF + wr * 64 + m * 16 + fr];
;                 const f32x4 g0 = acc[ai][0][m][0] * ri, g1 = acc[ai][0][m][1] * ri, u0 = acc[ai][1][m][0] * ri, u1 = acc[ai][1][m][1] * ri;
;                 u32x4 w;
;                 w.x = pg8::cvt_pk_bf16(silu_mul(g0[0], u0[0]), silu_mul(g0[1], u0[1])); w.y = pg8::cvt_pk_bf16(silu_mul(g0[2], u0[2]), silu_mul(g0[3], u0[3]));
;                 w.z = pg8::cvt_pk_bf16(silu_mul(g1[0], u1[0]), silu_mul(g1[1], u1[1])); w.w = pg8::cvt_pk_bf16(silu_mul(g1[2], u1[2]), silu_mul(g1[3], u1[3]));
;                 *(u32x4*)(O + (size_t)row * DFF + col0) = w;
	v_rcp_f32_e32 v217, v217
	v_cvt_pk_bf16_f32 v227, v230, v231
	v_pk_mul_f32 v[218:219], v[218:219], v[216:217]
	v_mul_f32_e32 v216, v92, v214
	v_mul_f32_e32 v217, v93, v214
	v_exp_f32_e32 v216, v216
	v_exp_f32_e32 v217, v217
	v_pk_mul_f32 v[230:231], v[92:93], v[84:85]
	v_pk_add_f32 v[216:217], v[216:217], 1.0 op_sel_hi:[1,0]
	v_pk_mul_f32 v[230:231], v[230:231], v[220:221] op_sel_hi:[1,0]
	v_rcp_f32_e32 v216, v216
	v_rcp_f32_e32 v217, v217
	v_cvt_pk_bf16_f32 v228, v218, v219
	v_pk_mul_f32 v[230:231], v[230:231], v[216:217]
	v_cvt_pk_bf16_f32 v229, v230, v231
	v_add_co_u32_e32 v224, vcc, 0x2c000, v212
	v_addc_co_u32_e32 v225, vcc, 0, v213, vcc
	global_store_dwordx4 v[224:225], v[226:229], off
	v_mul_f32_e32 v214, 0xbfb8aa3b, v205
	v_mul_f32_e32 v220, v205, v205
	v_mul_f32_e32 v216, v76, v214
	v_mul_f32_e32 v217, v77, v214
	v_exp_f32_e32 v216, v216
	v_exp_f32_e32 v217, v217
	v_pk_mul_f32 v[218:219], v[76:77], v[68:69]
	v_pk_add_f32 v[216:217], v[216:217], 1.0 op_sel_hi:[1,0]
	v_pk_mul_f32 v[218:219], v[218:219], v[220:221] op_sel_hi:[1,0]
	v_rcp_f32_e32 v216, v216
	v_rcp_f32_e32 v217, v217
	s_nop 0
	v_pk_mul_f32 v[218:219], v[218:219], v[216:217]
	v_mul_f32_e32 v216, v78, v214
	v_mul_f32_e32 v217, v79, v214
	v_exp_f32_e32 v216, v216
	v_exp_f32_e32 v217, v217
	v_pk_mul_f32 v[230:231], v[78:79], v[70:71]
	v_pk_add_f32 v[216:217], v[216:217], 1.0 op_sel_hi:[1,0]
	v_pk_mul_f32 v[230:231], v[230:231], v[220:221] op_sel_hi:[1,0]
	v_rcp_f32_e32 v216, v216
	v_rcp_f32_e32 v217, v217
	v_cvt_pk_bf16_f32 v226, v218, v219
	v_pk_mul_f32 v[230:231], v[230:231], v[216:217]
	v_mul_f32_e32 v216, v72, v214
	v_mul_f32_e32 v217, v73, v214
	v_exp_f32_e32 v216, v216
	v_exp_f32_e32 v217, v217
	v_pk_mul_f32 v[218:219], v[72:73], v[64:65]
	v_pk_add_f32 v[216:217], v[216:217], 1.0 op_sel_hi:[1,0]
	v_pk_mul_f32 v[218:219], v[218:219], v[220:221] op_sel_hi:[1,0]
	v_rcp_f32_e32 v216, v216
	v_rcp_f32_e32 v217, v217
	v_cvt_pk_bf16_f32 v227, v230, v231
	v_pk_mul_f32 v[218:219], v[218:219], v[216:217]
	v_mul_f32_e32 v216, v74, v214
	v_mul_f32_e32 v217, v75, v214
	v_exp_f32_e32 v216, v216
	v_exp_f32_e32 v217, v217
	v_pk_mul_f32 v[230:231], v[74:75], v[66:67]
	v_pk_add_f32 v[216:217], v[216:217], 1.0 op_sel_hi:[1,0]
	v_pk_mul_f32 v[230:231], v[230:231], v[220:221] op_sel_hi:[1,0]
	v_rcp_f32_e32 v216, v216
	v_rcp_f32_e32 v217, v217
	v_cvt_pk_bf16_f32 v228, v218, v219
	v_pk_mul_f32 v[230:231], v[230:231], v[216:217]
	v_cvt_pk_bf16_f32 v229, v230, v231
	v_add_co_u32_e32 v224, vcc, 0x42000, v212
	v_addc_co_u32_e32 v225, vcc, 0, v213, vcc
	global_store_dwordx4 v[224:225], v[226:229], off
	v_mul_f32_e32 v214, 0xbfb8aa3b, v206
	v_mul_f32_e32 v220, v206, v206
	v_mul_f32_e32 v216, v60, v214
	v_mul_f32_e32 v217, v61, v214
	v_exp_f32_e32 v216, v216
	v_exp_f32_e32 v217, v217
	v_pk_mul_f32 v[218:219], v[60:61], v[52:53]
	v_pk_add_f32 v[216:217], v[216:217], 1.0 op_sel_hi:[1,0]
	v_pk_mul_f32 v[218:219], v[218:219], v[220:221] op_sel_hi:[1,0]
	v_rcp_f32_e32 v216, v216
	v_rcp_f32_e32 v217, v217
	s_nop 0
	v_pk_mul_f32 v[218:219], v[218:219], v[216:217]
	v_mul_f32_e32 v216, v62, v214
	v_mul_f32_e32 v217, v63, v214
	v_exp_f32_e32 v216, v216
	v_exp_f32_e32 v217, v217
	v_pk_mul_f32 v[230:231], v[62:63], v[54:55]
	v_pk_add_f32 v[216:217], v[216:217], 1.0 op_sel_hi:[1,0]
	v_pk_mul_f32 v[230:231], v[230:231], v[220:221] op_sel_hi:[1,0]
	v_rcp_f32_e32 v216, v216
	v_rcp_f32_e32 v217, v217
	v_cvt_pk_bf16_f32 v226, v218, v219
	v_pk_mul_f32 v[230:231], v[230:231], v[216:217]
	v_mul_f32_e32 v216, v56, v214
	v_mul_f32_e32 v217, v57, v214
	v_exp_f32_e32 v216, v216
	v_exp_f32_e32 v217, v217
	v_pk_mul_f32 v[218:219], v[56:57], v[48:49]
	v_pk_add_f32 v[216:217], v[216:217], 1.0 op_sel_hi:[1,0]
	v_pk_mul_f32 v[218:219], v[218:219], v[220:221] op_sel_hi:[1,0]
	v_rcp_f32_e32 v216, v216
	v_rcp_f32_e32 v217, v217
	v_cvt_pk_bf16_f32 v227, v230, v231
	v_pk_mul_f32 v[218:219], v[218:219], v[216:217]
	v_mul_f32_e32 v216, v58, v214
	v_mul_f32_e32 v217, v59, v214
	v_exp_f32_e32 v216, v216
	v_exp_f32_e32 v217, v217
	v_pk_mul_f32 v[230:231], v[58:59], v[50:51]
	v_pk_add_f32 v[216:217], v[216:217], 1.0 op_sel_hi:[1,0]
	v_pk_mul_f32 v[230:231], v[230:231], v[220:221] op_sel_hi:[1,0]
	v_rcp_f32_e32 v216, v216
	v_rcp_f32_e32 v217, v217
	v_cvt_pk_bf16_f32 v228, v218, v219
	v_pk_mul_f32 v[230:231], v[230:231], v[216:217]
	v_cvt_pk_bf16_f32 v229, v230, v231
	v_add_co_u32_e32 v224, vcc, 0xb0000, v212
	v_addc_co_u32_e32 v225, vcc, 0, v213, vcc
	global_store_dwordx4 v[224:225], v[226:229], off
	v_mul_f32_e32 v214, 0xbfb8aa3b, v207
	v_mul_f32_e32 v220, v207, v207
	v_mul_f32_e32 v216, v44, v214
	v_mul_f32_e32 v217, v45, v214
	v_exp_f32_e32 v216, v216
	v_exp_f32_e32 v217, v217
	v_pk_mul_f32 v[218:219], v[44:45], v[36:37]
	v_pk_add_f32 v[216:217], v[216:217], 1.0 op_sel_hi:[1,0]
	v_pk_mul_f32 v[218:219], v[218:219], v[220:221] op_sel_hi:[1,0]
	v_rcp_f32_e32 v216, v216
	v_rcp_f32_e32 v217, v217
	s_nop 0
	v_pk_mul_f32 v[218:219], v[218:219], v[216:217]
	v_mul_f32_e32 v216, v46, v214
	v_mul_f32_e32 v217, v47, v214
	v_exp_f32_e32 v216, v216
	v_exp_f32_e32 v217, v217
	v_pk_mul_f32 v[230:231], v[46:47], v[38:39]
	v_pk_add_f32 v[216:217], v[216:217], 1.0 op_sel_hi:[1,0]
; __device__ __forceinline__ unsigned cvt_pk_bf16(float lo, float hi) { unsigned r; asm volatile("v_cvt_pk_bf16_f32 %0, %1, %2" : "=v"(r) : "v"(lo), "v"(hi)); return r; }
; #define PG8_BAR __builtin_amdgcn_s_barrier()
; template <class Epi, class Sched, bool ALIGN_EPI = false, bool SP2 = false, bool HALFM = false>
; __device__ __forceinline__ void gemm_phase(PG8_LAS unsigned char* lds, const Gemm g, const Sched& S, const Epi& E) {
;     ...
;         if (!has_next) break;
; #pragma unroll
;         for (int a = 0; a < 2; ++a)
; #pragma unroll
;             for (int b = 0; b < 2; ++b)
; #pragma unroll
;                 for (int m = 0; m < 4; ++m)
; #pragma unroll
;                     for (int n = 0; n < 2; ++n) acc[a][b][m][n] = (f32x4){0.f, 0.f, 0.f, 0.f};
;         cur = nxt; cA = nA; cB = nB; ++ui;
;         if constexpr (ALIGN_EPI) { if (wr == 1) PG8_BAR; }
;     __device__ __forceinline__ void operator()(const f32x4 (&acc)[2][2][4][2], const Unit& u, int wr, int wc, int fr, int fq) const {
;     ...
;             for (int m = 0; m < 4; ++m) {
;                 const int row = row0 + ai * HALF + m * 16; const float ri = tab[u.par * 256 + ai * HALF + wr * 64 + m * 16 + fr];
;                 const f32x4 g0 = acc[ai][0][m][0] * ri, g1 = acc[ai][0][m][1] * ri, u0 = acc[ai][1][m][0] * ri, u1 = acc[ai][1][m][1] * ri;
;                 u32x4 w;
;                 w.x = pg8::cvt_pk_bf16(silu_mul(g0[0], u0[0]), silu_mul(g0[1], u0[1])); w.y = pg8::cvt_pk_bf16(silu_mul(g0[2], u0[2]), silu_mul(g0[3], u0[3]));
;                 w.z = pg8::cvt_pk_bf16(silu_mul(g1[0], u1[0]), silu_mul(g1[1], u1[1])); w.w = pg8::cvt_pk_bf16(silu_mul(g1[2], u1[2]), silu_mul(g1[3], u1[3]));
;                 *(u32x4*)(O + (size_t)row * DFF + col0) = w;
;                 if (m & 1) asm volatile("" ::: "memory");
;             }
	v_pk_mul_f32 v[230:231], v[230:231], v[220:221] op_sel_hi:[1,0]
	v_rcp_f32_e32 v216, v216
	v_rcp_f32_e32 v217, v217
	v_cvt_pk_bf16_f32 v226, v218, v219
	v_pk_mul_f32 v[230:231], v[230:231], v[216:217]
	v_mul_f32_e32 v216, v40, v214
	v_mul_f32_e32 v217, v41, v214
	v_exp_f32_e32 v216, v216
	v_exp_f32_e32 v217, v217
	v_pk_mul_f32 v[218:219], v[40:41], v[32:33]
	v_pk_add_f32 v[216:217], v[216:217], 1.0 op_sel_hi:[1,0]
	v_pk_mul_f32 v[218:219], v[218:219], v[220:221] op_sel_hi:[1,0]
	v_rcp_f32_e32 v216, v216
	v_rcp_f32_e32 v217, v217
	v_cvt_pk_bf16_f32 v227, v230, v231
	v_pk_mul_f32 v[218:219], v[218:219], v[216:217]
	v_mul_f32_e32 v216, v42, v214
	v_mul_f32_e32 v217, v43, v214
	v_exp_f32_e32 v216, v216
	v_exp_f32_e32 v217, v217
	v_pk_mul_f32 v[230:231], v[42:43], v[34:35]
	v_pk_add_f32 v[216:217], v[216:217], 1.0 op_sel_hi:[1,0]
	v_pk_mul_f32 v[230:231], v[230:231], v[220:221] op_sel_hi:[1,0]
	v_rcp_f32_e32 v216, v216
	v_rcp_f32_e32 v217, v217
	v_cvt_pk_bf16_f32 v228, v218, v219
	v_pk_mul_f32 v[230:231], v[230:231], v[216:217]
	v_cvt_pk_bf16_f32 v229, v230, v231
	v_add_co_u32_e32 v224, vcc, 0xc6000, v212
	v_addc_co_u32_e32 v225, vcc, 0, v213, vcc
	global_store_dwordx4 v[224:225], v[226:229], off
	v_mul_f32_e32 v214, 0xbfb8aa3b, v208
	v_mul_f32_e32 v220, v208, v208
	v_mul_f32_e32 v216, v28, v214
	v_mul_f32_e32 v217, v29, v214
	v_exp_f32_e32 v216, v216
	v_exp_f32_e32 v217, v217
	v_pk_mul_f32 v[218:219], v[28:29], v[20:21]
	v_pk_add_f32 v[216:217], v[216:217], 1.0 op_sel_hi:[1,0]
	v_pk_mul_f32 v[218:219], v[218:219], v[220:221] op_sel_hi:[1,0]
	v_rcp_f32_e32 v216, v216
	v_rcp_f32_e32 v217, v217
	s_nop 0
	v_pk_mul_f32 v[218:219], v[218:219], v[216:217]
	v_mul_f32_e32 v216, v30, v214
	v_mul_f32_e32 v217, v31, v214
	v_exp_f32_e32 v216, v216
	v_exp_f32_e32 v217, v217
	v_pk_mul_f32 v[230:231], v[30:31], v[22:23]
	v_pk_add_f32 v[216:217], v[216:217], 1.0 op_sel_hi:[1,0]
	v_pk_mul_f32 v[230:231], v[230:231], v[220:221] op_sel_hi:[1,0]
	v_rcp_f32_e32 v216, v216
	v_rcp_f32_e32 v217, v217
	v_cvt_pk_bf16_f32 v226, v218, v219
	v_pk_mul_f32 v[230:231], v[230:231], v[216:217]
	v_mul_f32_e32 v216, v24, v214
	v_mul_f32_e32 v217, v25, v214
	v_exp_f32_e32 v216, v216
	v_exp_f32_e32 v217, v217
	v_pk_mul_f32 v[218:219], v[24:25], v[16:17]
	v_pk_add_f32 v[216:217], v[216:217], 1.0 op_sel_hi:[1,0]
	v_pk_mul_f32 v[218:219], v[218:219], v[220:221] op_sel_hi:[1,0]
	v_rcp_f32_e32 v216, v216
	v_rcp_f32_e32 v217, v217
	v_cvt_pk_bf16_f32 v227, v230, v231
	v_pk_mul_f32 v[218:219], v[218:219], v[216:217]
	v_mul_f32_e32 v216, v26, v214
	v_mul_f32_e32 v217, v27, v214
	v_exp_f32_e32 v216, v216
	v_exp_f32_e32 v217, v217
	v_pk_mul_f32 v[230:231], v[26:27], v[18:19]
	v_pk_add_f32 v[216:217], v[216:217], 1.0 op_sel_hi:[1,0]
	v_pk_mul_f32 v[230:231], v[230:231], v[220:221] op_sel_hi:[1,0]
	v_rcp_f32_e32 v216, v216
	v_rcp_f32_e32 v217, v217
	v_cvt_pk_bf16_f32 v228, v218, v219
	v_pk_mul_f32 v[230:231], v[230:231], v[216:217]
	v_cvt_pk_bf16_f32 v229, v230, v231
	v_add_co_u32_e32 v224, vcc, 0xdc000, v212
	v_addc_co_u32_e32 v225, vcc, 0, v213, vcc
	global_store_dwordx4 v[224:225], v[226:229], off
	v_mul_f32_e32 v214, 0xbfb8aa3b, v209
	v_mul_f32_e32 v220, v209, v209
	v_mul_f32_e32 v216, v12, v214
	v_mul_f32_e32 v217, v13, v214
	v_exp_f32_e32 v216, v216
	v_exp_f32_e32 v217, v217
	v_pk_mul_f32 v[218:219], v[12:13], v[4:5]
	v_pk_add_f32 v[216:217], v[216:217], 1.0 op_sel_hi:[1,0]
	v_pk_mul_f32 v[218:219], v[218:219], v[220:221] op_sel_hi:[1,0]
	v_rcp_f32_e32 v216, v216
	v_rcp_f32_e32 v217, v217
	s_nop 0
	v_pk_mul_f32 v[218:219], v[218:219], v[216:217]
	v_mul_f32_e32 v216, v14, v214
	v_mul_f32_e32 v217, v15, v214
	v_exp_f32_e32 v216, v216
	v_exp_f32_e32 v217, v217
	v_pk_mul_f32 v[230:231], v[14:15], v[6:7]
	v_pk_add_f32 v[216:217], v[216:217], 1.0 op_sel_hi:[1,0]
	v_pk_mul_f32 v[230:231], v[230:231], v[220:221] op_sel_hi:[1,0]
	v_rcp_f32_e32 v216, v216
	v_rcp_f32_e32 v217, v217
	v_cvt_pk_bf16_f32 v226, v218, v219
	v_pk_mul_f32 v[230:231], v[230:231], v[216:217]
	v_mul_f32_e32 v216, v8, v214
	v_mul_f32_e32 v217, v9, v214
	v_exp_f32_e32 v216, v216
	v_exp_f32_e32 v217, v217
	v_pk_mul_f32 v[218:219], v[8:9], v[0:1]
	v_pk_add_f32 v[216:217], v[216:217], 1.0 op_sel_hi:[1,0]
	v_pk_mul_f32 v[218:219], v[218:219], v[220:221] op_sel_hi:[1,0]
	v_rcp_f32_e32 v216, v216
	v_rcp_f32_e32 v217, v217
	v_cvt_pk_bf16_f32 v227, v230, v231
	v_pk_mul_f32 v[218:219], v[218:219], v[216:217]
	v_mul_f32_e32 v216, v10, v214
	v_mul_f32_e32 v217, v11, v214
	v_exp_f32_e32 v216, v216
	v_exp_f32_e32 v217, v217
	v_pk_mul_f32 v[230:231], v[10:11], v[2:3]
	v_pk_add_f32 v[216:217], v[216:217], 1.0 op_sel_hi:[1,0]
	v_pk_mul_f32 v[230:231], v[230:231], v[220:221] op_sel_hi:[1,0]
	v_rcp_f32_e32 v216, v216
	v_rcp_f32_e32 v217, v217
	v_cvt_pk_bf16_f32 v228, v218, v219
	v_pk_mul_f32 v[230:231], v[230:231], v[216:217]
	v_cvt_pk_bf16_f32 v229, v230, v231
	v_add_co_u32_e32 v224, vcc, 0xf2000, v212
	v_addc_co_u32_e32 v225, vcc, 0, v213, vcc
	global_store_dwordx4 v[224:225], v[226:229], off
	s_andn2_b64 vcc, exec, s[16:17]
	s_mov_b64 s[18:19], -1
	s_cbranch_vccnz .LBB0_174
	s_andn2_b64 vcc, exec, s[0:1]
	s_cbranch_vccnz .LBB0_173
	s_barrier
	s_branch .LBB0_173
